# known-value deletion: h1 rescale test flag set by SALU on the fast path, v_cmp only in the rescale path (on top of deferred row-sum reduce)
# speedup vs baseline: 1.0063x; 1.0058x over previous
; DI void finishSM(f32x16& p0, f32x16& p1, float alpha, float& l_reg, bf16x8& pa0, bf16x8& pa1, bf16x8& pa2, bf16x8& pa3) {
; #pragma unroll
;     for (int r = 0; r < 16; ++r) p1[r] = __builtin_amdgcn_exp2f(p1[r]);
;     float ps = 0;
; #pragma unroll
;     for (int r = 0; r < 16; ++r) ps += p0[r];
; #pragma unroll
;     for (int r = 0; r < 16; ++r) ps += p1[r];
;     { auto rr = __builtin_amdgcn_permlane32_swap(__float_as_uint(ps), __float_as_uint(ps), false, false);
;       ps = __uint_as_float(rr[0]) + __uint_as_float(rr[1]); }
;     l_reg = l_reg * alpha + ps;
;     ...
;     PK4(p0, 0, pa0); PK4(p0, 8, pa1); PK4(p1, 0, pa2); PK4(p1, 8, pa3);
;     ...
; }
; DI void qkt(f32x16& p0, f32x16& p1, const char* Ks, const bf16x8* qr, const f32x16& negm, int r32, int hi) {
;     { const bf16x8 b0 = *reinterpret_cast<const bf16x8*>(Ks + KSWZ(r32, hi * 16));
;       const bf16x8 b1 = *reinterpret_cast<const bf16x8*>(Ks + KSWZ(32 + r32, hi * 16));
;       p0 = __builtin_amdgcn_mfma_f32_32x32x16_bf16(b0, qr[0], negm, 0, 0, 0);
;       p1 = __builtin_amdgcn_mfma_f32_32x32x16_bf16(b1, qr[0], negm, 0, 0, 0); }
; #pragma unroll
;     for (int d0 = 1; d0 < 4; ++d0) { const int cb = (d0 * 16 + hi * 8) * 2;
;         const bf16x8 b0 = *reinterpret_cast<const bf16x8*>(Ks + KSWZ(r32, cb));
;         const bf16x8 b1 = *reinterpret_cast<const bf16x8*>(Ks + KSWZ(32 + r32, cb));
;         p0 = __builtin_amdgcn_mfma_f32_32x32x16_bf16(b0, qr[d0], p0, 0, 0, 0);
;         p1 = __builtin_amdgcn_mfma_f32_32x32x16_bf16(b1, qr[d0], p1, 0, 0, 0); }
; }
; DI int v_st(int k, int c) { const int kk = (k & ~0xC) | ((k & 4) << 1) | ((k & 8) >> 1); return ((kk >> 3) * 4 + (c >> 5)) * 512 + ((kk & 7) * 32 + (c & 31)) * 2; }
; DI int v_rd_base(int lane) { return ((lane & 3) << 3) | (((lane >> 2) & 3) << 6) | (((lane >> 4) & 1) << 5) | (((lane >> 5) & 1) << 8); }
; template <int OFF> DI s16x4 tr_read(int vb) { s16x4 r; asm volatile("ds_read_b64_tr_b16 %0, %1 offset:%2" : "=&v"(r) : "v"(vb), "i"(OFF) : "memory"); return r; }
; template <int D0> DI void pv_one(f32x16& od, int vb, bf16x8 pa0, bf16x8 pa1, bf16x8 pa2, bf16x8 pa3) {
;     const s16x4 l0 = tr_read<v_rd_off(D0, 0, 0)>(vb), h0 = tr_read<v_rd_off(D0, 0, 1)>(vb), l1 = tr_read<v_rd_off(D0, 1, 0)>(vb), h1 = tr_read<v_rd_off(D0, 1, 1)>(vb);
.LBB0_1038:
	ds_read_b128 v[80:83], v217 offset:40960
	ds_read_b128 v[84:87], v217 offset:45056
	v_exp_f32_e32 v88, v96
	v_exp_f32_e32 v89, v97
	v_exp_f32_e32 v90, v98
	s_waitcnt lgkmcnt(1)
	v_mfma_f32_32x32x16_bf16 v[128:143], v[80:83], v[148:151], v[64:79]
	v_exp_f32_e32 v91, v99
	v_exp_f32_e32 v92, v100
	v_exp_f32_e32 v93, v101
	v_exp_f32_e32 v94, v102
	v_exp_f32_e32 v95, v103
	v_exp_f32_e32 v96, v104
	v_exp_f32_e32 v97, v105
	s_waitcnt lgkmcnt(0)
	v_mfma_f32_32x32x16_bf16 v[112:127], v[84:87], v[148:151], v[64:79]
	ds_read_b128 v[80:83], v218 offset:40960
	ds_read_b128 v[84:87], v218 offset:45056
	v_exp_f32_e32 v98, v106
	v_exp_f32_e32 v99, v107
	v_exp_f32_e32 v100, v108
	v_exp_f32_e32 v101, v109
	v_exp_f32_e32 v102, v110
	v_exp_f32_e32 v103, v111
	s_waitcnt lgkmcnt(1)
	v_mfma_f32_32x32x16_bf16 v[128:143], v[80:83], v[144:147], v[128:143]
	s_waitcnt lgkmcnt(0)
	v_mfma_f32_32x32x16_bf16 v[112:127], v[84:87], v[144:147], v[112:127]
	ds_read_b128 v[80:83], v219 offset:40960
	ds_read_b128 v[84:87], v219 offset:45056
	s_waitcnt lgkmcnt(1)
	v_mfma_f32_32x32x16_bf16 v[128:143], v[80:83], v[152:155], v[128:143]
	s_waitcnt lgkmcnt(0)
	v_mfma_f32_32x32x16_bf16 v[112:127], v[84:87], v[152:155], v[112:127]
	ds_read_b128 v[80:83], v216 offset:40960
	ds_read_b128 v[84:87], v216 offset:45056
	s_waitcnt lgkmcnt(1)
	v_mfma_f32_32x32x16_bf16 v[128:143], v[80:83], v[156:159], v[128:143]
	v_add_f32_e32 v80, v209, v207
	v_add_f32_e32 v80, v183, v80
	v_add_f32_e32 v80, v208, v80
	v_add_f32_e32 v80, v181, v80
	v_add_f32_e32 v80, v206, v80
	v_add_f32_e32 v80, v180, v80
	v_add_f32_e32 v80, v182, v80
	v_add_f32_e32 v80, v173, v80
	v_add_f32_e32 v80, v175, v80
	v_add_f32_e32 v80, v172, v80
	v_add_f32_e32 v80, v174, v80
	v_add_f32_e32 v80, v177, v80
	v_add_f32_e32 v80, v179, v80
	v_add_f32_e32 v80, v176, v80
	v_add_f32_e32 v80, v178, v80
	v_add_f32_e32 v80, v88, v80
	v_add_f32_e32 v80, v89, v80
	v_add_f32_e32 v80, v90, v80
	v_add_f32_e32 v80, v91, v80
	v_add_f32_e32 v80, v92, v80
	v_add_f32_e32 v80, v93, v80
	v_add_f32_e32 v80, v94, v80
	v_add_f32_e32 v80, v95, v80
	v_add_f32_e32 v80, v96, v80
	v_add_f32_e32 v80, v97, v80
	s_waitcnt lgkmcnt(0)
	v_mfma_f32_32x32x16_bf16 v[112:127], v[84:87], v[156:159], v[112:127]
	v_add_f32_e32 v80, v98, v80
	v_add_f32_e32 v80, v99, v80
	v_add_f32_e32 v80, v100, v80
	v_add_f32_e32 v80, v101, v80
	v_add_f32_e32 v80, v102, v80
	v_add_f32_e32 v222, v103, v80
	v_cvt_pk_bf16_f32 v80, v207, v209
	v_cvt_pk_bf16_f32 v81, v183, v208
	v_cvt_pk_bf16_f32 v82, v181, v206
	v_cvt_pk_bf16_f32 v83, v180, v182
	v_cvt_pk_bf16_f32 v84, v173, v175
	v_cvt_pk_bf16_f32 v85, v172, v174
	v_cvt_pk_bf16_f32 v86, v177, v179
	v_cvt_pk_bf16_f32 v87, v176, v178
	v_cvt_pk_bf16_f32 v88, v88, v89
	v_cvt_pk_bf16_f32 v89, v90, v91
	v_cvt_pk_bf16_f32 v90, v92, v93
	v_cvt_pk_bf16_f32 v91, v94, v95
	v_cvt_pk_bf16_f32 v92, v96, v97
	v_cvt_pk_bf16_f32 v93, v98, v99
	v_cvt_pk_bf16_f32 v94, v100, v101
	v_cvt_pk_bf16_f32 v95, v102, v103
	global_load_dwordx4 v[172:175], v203, s[98:99]
	global_load_dwordx4 v[176:179], v204, s[98:99]
	global_load_dwordx4 v[180:183], v202, s[100:101]
	s_add_u32 s98, s98, 0x20000
	s_addc_u32 s99, s99, 0
	s_add_u32 s100, s100, 0x20000
	s_addc_u32 s101, s101, 0
	ds_read_b64_tr_b16 v[96:97], v220 offset:0
	ds_read_b64_tr_b16 v[98:99], v220 offset:0x100
	ds_read_b64_tr_b16 v[100:101], v220 offset:0x1000
	ds_read_b64_tr_b16 v[102:103], v220 offset:0x1100
	ds_read_b64_tr_b16 v[104:105], v220 offset:0x2000
	ds_read_b64_tr_b16 v[106:107], v220 offset:0x2100
	ds_read_b64_tr_b16 v[108:109], v220 offset:0x3000
	ds_read_b64_tr_b16 v[110:111], v220 offset:0x3100
	s_waitcnt lgkmcnt(0)
	s_nop 0
	v_mfma_f32_32x32x16_bf16 v[48:63], v[80:83], v[96:99], v[48:63]
	ds_read_b64_tr_b16 v[96:97], v220 offset:0x200
	ds_read_b64_tr_b16 v[98:99], v220 offset:0x300
	v_mfma_f32_32x32x16_bf16 v[48:63], v[84:87], v[100:103], v[48:63]
	ds_read_b64_tr_b16 v[100:101], v220 offset:0x1200
	ds_read_b64_tr_b16 v[102:103], v220 offset:0x1300
	v_mfma_f32_32x32x16_bf16 v[48:63], v[88:91], v[104:107], v[48:63]
	ds_read_b64_tr_b16 v[104:105], v220 offset:0x2200
	ds_read_b64_tr_b16 v[106:107], v220 offset:0x2300
	v_mfma_f32_32x32x16_bf16 v[48:63], v[92:95], v[108:111], v[48:63]
	ds_read_b64_tr_b16 v[108:109], v220 offset:0x3200
	ds_read_b64_tr_b16 v[110:111], v220 offset:0x3300
	s_waitcnt lgkmcnt(0)
	v_mfma_f32_32x32x16_bf16 v[32:47], v[80:83], v[96:99], v[32:47]
	ds_read_b64_tr_b16 v[96:97], v220 offset:0x400
	ds_read_b64_tr_b16 v[98:99], v220 offset:0x500
	v_mfma_f32_32x32x16_bf16 v[32:47], v[84:87], v[100:103], v[32:47]
	ds_read_b64_tr_b16 v[100:101], v220 offset:0x1400
	ds_read_b64_tr_b16 v[102:103], v220 offset:0x1500
	v_mfma_f32_32x32x16_bf16 v[32:47], v[88:91], v[104:107], v[32:47]
	ds_read_b64_tr_b16 v[104:105], v220 offset:0x2400
	ds_read_b64_tr_b16 v[106:107], v220 offset:0x2500
	v_mfma_f32_32x32x16_bf16 v[32:47], v[92:95], v[108:111], v[32:47]
	ds_read_b64_tr_b16 v[108:109], v220 offset:0x3400
	ds_read_b64_tr_b16 v[110:111], v220 offset:0x3500
	s_waitcnt lgkmcnt(0)
	v_mfma_f32_32x32x16_bf16 v[16:31], v[80:83], v[96:99], v[16:31]
	ds_read_b64_tr_b16 v[96:97], v220 offset:0x600
	ds_read_b64_tr_b16 v[98:99], v220 offset:0x700
	v_mfma_f32_32x32x16_bf16 v[16:31], v[84:87], v[100:103], v[16:31]
	ds_read_b64_tr_b16 v[100:101], v220 offset:0x1600
	ds_read_b64_tr_b16 v[102:103], v220 offset:0x1700
	v_mfma_f32_32x32x16_bf16 v[16:31], v[88:91], v[104:107], v[16:31]
	ds_read_b64_tr_b16 v[104:105], v220 offset:0x2600
	ds_read_b64_tr_b16 v[106:107], v220 offset:0x2700
	v_mfma_f32_32x32x16_bf16 v[16:31], v[92:95], v[108:111], v[16:31]
	ds_read_b64_tr_b16 v[108:109], v220 offset:0x3600
	ds_read_b64_tr_b16 v[110:111], v220 offset:0x3700
	s_waitcnt lgkmcnt(0)
	v_mfma_f32_32x32x16_bf16 v[0:15], v[80:83], v[96:99], v[0:15]
	v_max_f32_e32 v80, v128, v129
	v_max3_f32 v80, v80, v130, v131
	v_max3_f32 v80, v80, v132, v133
	v_max3_f32 v80, v80, v134, v135
	v_max3_f32 v80, v80, v136, v137
	v_mfma_f32_32x32x16_bf16 v[0:15], v[84:87], v[100:103], v[0:15]
	v_max3_f32 v80, v80, v138, v139
	v_max3_f32 v80, v80, v140, v141
	v_max3_f32 v80, v80, v142, v143
	v_max3_f32 v80, v80, v112, v113
	v_max3_f32 v80, v80, v114, v115
	v_max3_f32 v80, v80, v116, v117
	v_max3_f32 v80, v80, v118, v119
	v_mfma_f32_32x32x16_bf16 v[0:15], v[88:91], v[104:107], v[0:15]
	v_max3_f32 v80, v80, v120, v121
	v_max3_f32 v80, v80, v122, v123
	v_max3_f32 v80, v80, v124, v125
	v_max3_f32 v80, v80, v126, v127
	v_mov_b32_e32 v81, v80
	s_nop 1
	v_permlane32_swap_b32_e32 v80, v81
	v_mfma_f32_32x32x16_bf16 v[0:15], v[92:95], v[108:111], v[0:15]
	v_max_f32_e32 v80, v80, v81
	v_cmp_ngt_f32_e32 vcc, s83, v200
	v_cmp_ge_f32_e64 s[8:9], s63, v80
	s_and_b64 s[4:5], vcc, s[8:9]
	s_cmp_eq_u64 s[4:5], exec
	s_cbranch_scc0 .LBB0_1057
	v_mov_b32_e32 v224, 1.0
	s_mov_b64 vcc, 0
; #define SWRITEA(b) do { *(bf16x8*)(V_lds + (b) * SHM_V + vst0) = vsA0; *(bf16x8*)(V_lds + (b) * SHM_V + vst1) = vsA1; *(bf16x8*)(K_lds + (b) * SHM_K + kst) = ksA; } while (0)
; #define SWAIT() asm volatile("s_waitcnt vmcnt(3)" ::: "memory")
; #define RESC(a) do { if (__any((a) < 1.f)) { if (hi == 0) al_l[r32] = (a); asm volatile("s_waitcnt lgkmcnt(0)" ::: "memory"); \
;     _Pragma("unroll") for (int d = 0; d < 4; ++d) _Pragma("unroll") for (int r = 0; r < 16; ++r) o[d][r] *= al_l[crow(r, hi)]; } } while (0)
; DI void attn_pass(const bf16_t* __restrict__ Qb, const bf16_t* __restrict__ Kh, const bf16_t* __restrict__ Vh, int seq, char* lds, f32x16 (&o)[4], float& l_out) {
;     ...
;         __syncthreads(); SWAIT(); SWRITEA(0);
;         RESC(alB); __syncthreads();
.LBB0_1040:
	s_barrier
	s_waitcnt vmcnt(3)
	s_waitcnt vmcnt(3)
	ds_write_b128 v214, v[160:163]
	ds_write_b128 v215, v[164:167]
	ds_write_b128 v213, v[168:171] offset:32768
	s_cbranch_vccz .LBB0_1044
	s_and_saveexec_b64 s[4:5], s[6:7]
	ds_write_b32 v212, v224 offset:49280
	s_or_b64 exec, exec, s[4:5]
	s_waitcnt lgkmcnt(0)
	v_add_u32_e32 v108, v211, v184
	ds_read_b128 v[96:99], v108 offset:49376
	ds_read_b128 v[100:103], v108 offset:49344
	ds_read_b128 v[104:107], v108 offset:49312
	ds_read_b128 v[108:111], v108 offset:49280
	s_waitcnt lgkmcnt(3)
	v_pk_mul_f32 v[60:61], v[60:61], v[96:97]
	s_waitcnt lgkmcnt(2)
	v_pk_mul_f32 v[56:57], v[56:57], v[100:101]
	s_waitcnt lgkmcnt(1)
	v_pk_mul_f32 v[52:53], v[52:53], v[104:105]
	v_pk_mul_f32 v[62:63], v[62:63], v[98:99]
	v_pk_mul_f32 v[58:59], v[58:59], v[102:103]
	v_pk_mul_f32 v[54:55], v[54:55], v[106:107]
	s_waitcnt lgkmcnt(0)
	v_pk_mul_f32 v[50:51], v[50:51], v[110:111]
	v_pk_mul_f32 v[48:49], v[48:49], v[108:109]
	v_pk_mul_f32 v[44:45], v[96:97], v[44:45]
	v_pk_mul_f32 v[40:41], v[100:101], v[40:41]
	v_pk_mul_f32 v[36:37], v[104:105], v[36:37]
	v_pk_mul_f32 v[46:47], v[98:99], v[46:47]
	v_pk_mul_f32 v[42:43], v[102:103], v[42:43]
	v_pk_mul_f32 v[38:39], v[106:107], v[38:39]
	v_pk_mul_f32 v[34:35], v[110:111], v[34:35]
	v_pk_mul_f32 v[32:33], v[108:109], v[32:33]
	v_pk_mul_f32 v[28:29], v[96:97], v[28:29]
	v_pk_mul_f32 v[24:25], v[100:101], v[24:25]
	v_pk_mul_f32 v[20:21], v[104:105], v[20:21]
	v_pk_mul_f32 v[30:31], v[98:99], v[30:31]
	v_pk_mul_f32 v[26:27], v[102:103], v[26:27]
	v_pk_mul_f32 v[22:23], v[106:107], v[22:23]
	v_pk_mul_f32 v[18:19], v[110:111], v[18:19]
	v_pk_mul_f32 v[16:17], v[108:109], v[16:17]
	v_pk_mul_f32 v[12:13], v[96:97], v[12:13]
	v_pk_mul_f32 v[8:9], v[100:101], v[8:9]
	v_pk_mul_f32 v[4:5], v[104:105], v[4:5]
	v_pk_mul_f32 v[14:15], v[98:99], v[14:15]
	v_pk_mul_f32 v[10:11], v[102:103], v[10:11]
	v_pk_mul_f32 v[6:7], v[106:107], v[6:7]
	v_pk_mul_f32 v[2:3], v[110:111], v[2:3]
	v_pk_mul_f32 v[0:1], v[108:109], v[0:1]

; DI void partialSM(f32x16& p0, f32x16& p1, float& m_reg, f32x16& negm, float& alpha) {
;     ...
;     { auto rr = __builtin_amdgcn_permlane32_swap(__float_as_uint(pmax), __float_as_uint(pmax), false, false);
;       pmax = fmaxf(__uint_as_float(rr[0]), __uint_as_float(rr[1])); }
;     const bool first = m_reg < -1e29f;
;     if (__builtin_expect(__all(!first && pmax <= THR2), 1)) { alpha = 1.f; }
;     else {
;         const float d = first ? pmax : fmaxf(pmax, 0.f);
;         alpha = first ? 0.f : __builtin_amdgcn_exp2f(-d);
;         m_reg = first ? pmax : m_reg + d;
; #pragma unroll
;         for (int r = 0; r < 16; ++r) { p0[r] -= d; p1[r] -= d; negm[r] = -m_reg; }
;     }
.LBB0_1057:
	v_max_f32_e32 v64, v80, v80
	v_max_f32_e32 v65, 0, v64
	v_cndmask_b32_e32 v64, v80, v65, vcc
	v_exp_f32_e64 v66, -v64
	v_add_f32_e32 v65, v200, v65
	v_cndmask_b32_e32 v200, v80, v65, vcc
	v_xor_b32_e32 v80, 0x80000000, v200
	v_cndmask_b32_e32 v224, 0, v66, vcc
	v_pk_add_f32 v[128:129], v[128:129], v[64:65] op_sel_hi:[1,0] neg_lo:[0,1] neg_hi:[0,1]
	v_pk_add_f32 v[130:131], v[130:131], v[64:65] op_sel_hi:[1,0] neg_lo:[0,1] neg_hi:[0,1]
	v_pk_add_f32 v[132:133], v[132:133], v[64:65] op_sel_hi:[1,0] neg_lo:[0,1] neg_hi:[0,1]
	v_pk_add_f32 v[134:135], v[134:135], v[64:65] op_sel_hi:[1,0] neg_lo:[0,1] neg_hi:[0,1]
	v_pk_add_f32 v[136:137], v[136:137], v[64:65] op_sel_hi:[1,0] neg_lo:[0,1] neg_hi:[0,1]
	v_pk_add_f32 v[138:139], v[138:139], v[64:65] op_sel_hi:[1,0] neg_lo:[0,1] neg_hi:[0,1]
	v_pk_add_f32 v[140:141], v[140:141], v[64:65] op_sel_hi:[1,0] neg_lo:[0,1] neg_hi:[0,1]
	v_pk_add_f32 v[142:143], v[142:143], v[64:65] op_sel_hi:[1,0] neg_lo:[0,1] neg_hi:[0,1]
	v_sub_f32_e32 v127, v127, v64
	v_sub_f32_e32 v126, v126, v64
	v_sub_f32_e32 v125, v125, v64
	v_sub_f32_e32 v124, v124, v64
	v_sub_f32_e32 v123, v123, v64
	v_sub_f32_e32 v122, v122, v64
	v_sub_f32_e32 v121, v121, v64
	v_sub_f32_e32 v120, v120, v64
	v_sub_f32_e32 v119, v119, v64
	v_sub_f32_e32 v118, v118, v64
	v_sub_f32_e32 v117, v117, v64
	v_sub_f32_e32 v116, v116, v64
	v_sub_f32_e32 v115, v115, v64
	v_sub_f32_e32 v114, v114, v64
	v_sub_f32_e32 v113, v113, v64
	v_sub_f32_e32 v112, v112, v64
	v_mov_b32_e32 v81, v80
	v_mov_b32_e32 v82, v80
	v_mov_b32_e32 v83, v80
	v_mov_b32_e32 v84, v80
	v_mov_b32_e32 v85, v80
	v_mov_b32_e32 v86, v80
	v_mov_b32_e32 v87, v80
	v_mov_b32_e32 v88, v80
	v_mov_b32_e32 v89, v80
	v_mov_b32_e32 v90, v80
	v_mov_b32_e32 v91, v80
	v_mov_b32_e32 v92, v80
	v_mov_b32_e32 v93, v80
	v_mov_b32_e32 v94, v80
	v_mov_b32_e32 v95, v80
	v_mov_b32_e32 v64, v80
	v_mov_b32_e32 v65, v80
	v_mov_b32_e32 v66, v80
	v_mov_b32_e32 v67, v80
	v_mov_b32_e32 v68, v80
	v_mov_b32_e32 v69, v80
	v_mov_b32_e32 v70, v80
	v_mov_b32_e32 v71, v80
	v_mov_b32_e32 v72, v80
	v_mov_b32_e32 v73, v80
	v_mov_b32_e32 v74, v80
	v_mov_b32_e32 v75, v80
	v_mov_b32_e32 v76, v80
	v_mov_b32_e32 v77, v80
	v_mov_b32_e32 v78, v80
	v_mov_b32_e32 v79, v80
	v_cmp_gt_f32_e32 vcc, 1.0, v224
	s_branch .LBB0_1040
